# SSD chunk loop: first two state-fragment LDS reads of each slab block issued before the previous block's intra-chunk section (into idle staging registers)
# baseline (speedup 1.0000x reference)
; __device__ __forceinline__ void ssd_item(const Params& P, const int pass, const int item, const int wvi) {
;     ...
;     const float tot = dir ? fcum[0] : fcum[127];
;     const float cum_i = fcum[it * 16 + fr];
;     const int ii = it * 16 + fr;
;     f32x4 y1[4], y2[4];
; #pragma unroll
;     for (int i = 0; i < 4; ++i) { y1[i] = f32x4{0.f, 0.f, 0.f, 0.f}; y2[i] = f32x4{0.f, 0.f, 0.f, 0.f}; }
;     {
;       const float dec = __expf(tot);
; #pragma unroll
;       for (int pt = 0; pt < 4; ++pt)
; #pragma unroll
;         for (int j = 0; j < 4; ++j) st[pt][j] *= dec;
;     }
; #pragma unroll
;     for (int kk = 0; kk < 4; ++kk) {
;       const int s0 = kk * 32 + fq * 8;
;       bf16x8 xf[4];
; #pragma unroll
;       for (int pt = 0; pt < 4; ++pt) {
;         const u16* xa = Xs + (kk * 32 + fq * 8 + (fr >> 2)) * LDX + pt * 16 + (fr & 3) * 4;
;         xf[pt] = cat8(ldtr(xa), ldtr(xa + 4 * LDX));
;       }
;       {
;         const u16* ba = Bs + (kk * 32 + fq * 8 + (fr >> 2)) * LDP + w * 16 + (fr & 3) * 4;
;         const s16x4 b0 = ldtr(ba), b1 = ldtr(ba + 4 * LDP);
;         const float4 wa = *(const float4*)(fww + s0), wb = *(const float4*)(fww + s0 + 4);
;         const bf16x8 af = pack8(bf2f((u16)b0[0]) * wa.x, bf2f((u16)b0[1]) * wa.y, bf2f((u16)b0[2]) * wa.z, bf2f((u16)b0[3]) * wa.w,
;                                 bf2f((u16)b1[0]) * wb.x, bf2f((u16)b1[1]) * wb.y, bf2f((u16)b1[2]) * wb.z, bf2f((u16)b1[3]) * wb.w);
; #pragma unroll
;         for (int pt = 0; pt < 4; ++pt) st[pt] = __builtin_amdgcn_mfma_f32_16x16x32_bf16(af, xf[pt], st[pt], 0, 0, 0);
;       }
;       if (kk >= kk_lo && kk <= kk_hi) {
;         const uint4 gq = (kk == 0) ? gq0 : (kk == 1) ? gq1 : (kk == 2) ? gq2 : gq3;
;         const float gv[8] = {bflo(gq.x), bfhi(gq.x), bflo(gq.y), bfhi(gq.y), bflo(gq.z), bfhi(gq.z), bflo(gq.w), bfhi(gq.w)};
;         float mv[8];
;         if (kk == (it >> 1)) {
;           const float4 ca = *(const float4*)(fcum + s0), cb = *(const float4*)(fcum + s0 + 4);
;           const float4 da = *(const float4*)(fdt + s0), db = *(const float4*)(fdt + s0 + 4);
;           const float cs[8] = {ca.x, ca.y, ca.z, ca.w, cb.x, cb.y, cb.z, cb.w};
;           const float ds[8] = {da.x, da.y, da.z, da.w, db.x, db.y, db.z, db.w};
; #pragma unroll
;           for (int e = 0; e < 8; ++e) {
;             const int ss = s0 + e;
.LBB0_657:
	v_lshl_add_u64 v[88:89], s[0:1], 2, v[162:163]
	global_load_dword v228, v[88:89], off
	s_add_i32 s25, s26, 0x11800
	s_add_i32 s23, s26, 0x11600
	s_add_i32 s24, s26, 0x11a00
	s_add_i32 vcc_lo, s26, 0x117fc
	s_and_b64 s[0:1], s[8:9], exec
	s_cselect_b32 s0, vcc_lo, s23
	v_mov_b32_e32 v88, s0
	ds_read_b32 v88, v88
	v_add_u32_e32 v235, s26, v232
	v_add_u32_e32 v233, s27, v232
	v_add_u32_e32 v121, v235, v220
	ds_read_b64_tr_b16 v[90:91], v121 offset:35392
	s_waitcnt lgkmcnt(1)
	v_mul_f32_e32 v88, 0x3fb8aa3b, v88
	v_exp_f32_e32 v132, v88
	v_lshl_add_u32 v120, v170, 2, s23
	s_andn2_b64 vcc, exec, s[6:7]
	v_pk_mul_f32 v[96:97], v[112:113], v[132:133] op_sel_hi:[1,0]
	v_add_u32_e32 v112, v233, v221
	ds_read_b64_tr_b16 v[88:89], v112
	v_lshl_add_u32 v113, v212, 2, s25
	v_pk_mul_f32 v[98:99], v[114:115], v[132:133] op_sel_hi:[1,0]
	ds_read_b128 v[92:95], v113
	ds_read_b64_tr_b16 v[116:117], v112 offset:1088
	ds_read_b64_tr_b16 v[122:123], v121 offset:35488
	ds_read_b128 v[112:115], v113 offset:16
	v_pk_mul_f32 v[110:111], v[110:111], v[132:133] op_sel_hi:[1,0]
	s_waitcnt lgkmcnt(4)
	v_and_b32_e32 v119, 0xffff0000, v88
	v_lshlrev_b32_e32 v118, 16, v88
	s_waitcnt lgkmcnt(3)
	v_pk_mul_f32 v[92:93], v[92:93], v[118:119]
	v_pk_mul_f32 v[108:109], v[108:109], v[132:133] op_sel_hi:[1,0]
	v_cvt_pk_bf16_f32 v128, v92, v93
	v_and_b32_e32 v93, 0xffff0000, v89
	v_lshlrev_b32_e32 v92, 16, v89
	v_pk_mul_f32 v[88:89], v[94:95], v[92:93]
	s_nop 0
	v_cvt_pk_bf16_f32 v129, v88, v89
	s_waitcnt lgkmcnt(2)
	v_and_b32_e32 v89, 0xffff0000, v116
	v_lshlrev_b32_e32 v88, 16, v116
	s_waitcnt lgkmcnt(0)
	v_pk_mul_f32 v[88:89], v[112:113], v[88:89]
	s_nop 0
	v_cvt_pk_bf16_f32 v130, v88, v89
	v_and_b32_e32 v89, 0xffff0000, v117
	v_lshlrev_b32_e32 v88, 16, v117
	v_pk_mul_f32 v[88:89], v[114:115], v[88:89]
	s_nop 0
	v_cvt_pk_bf16_f32 v131, v88, v89
	ds_read_b32 v161, v120
	ds_read_b64_tr_b16 v[88:89], v121 offset:34816
	ds_read_b64_tr_b16 v[92:93], v121 offset:34848
	ds_read_b64_tr_b16 v[124:125], v121 offset:34880
	ds_read_b64_tr_b16 v[94:95], v121 offset:35424
	ds_read_b64_tr_b16 v[126:127], v121 offset:35456
	ds_read_b64_tr_b16 v[120:121], v121 offset:34912
	s_waitcnt lgkmcnt(5)
	v_mfma_f32_16x16x32_bf16 v[112:115], v[128:131], v[88:91], v[96:99]
	s_nop 2
	v_mul_f32_e64 v98, v102, v132
	v_mul_f32_e64 v99, v103, v132
	v_pk_mul_f32 v[96:97], v[100:101], v[132:133] op_sel_hi:[1,0]
	v_pk_mul_f32 v[100:101], v[106:107], v[132:133] op_sel_hi:[1,0]
	s_waitcnt lgkmcnt(0)
	v_mfma_f32_16x16x32_bf16 v[108:111], v[128:131], v[120:123], v[108:111]
	v_mfma_f32_16x16x32_bf16 v[116:119], v[128:131], v[92:95], v[96:99]
	s_nop 2
	v_mul_f32_e64 v98, v104, v132
	v_mul_f32_e64 v99, v105, v132
	s_nop 1
	v_mfma_f32_16x16x32_bf16 v[104:107], v[128:131], v[124:127], v[98:101]
	v_lshl_add_u32 v234, v212, 1, s26
	v_add_u32_e32 v234, v234, v157
	ds_read_b128 v[0:3], v234 offset:53248
	ds_read_b128 v[4:7], v234 offset:57600
	s_cbranch_vccnz .LBB0_665
	v_readlane_b32 vcc_lo, v245, 10
	v_readlane_b32 vcc_hi, v245, 11
	v_lshlrev_b32_e32 v100, 16, v84
	v_and_b32_e32 v101, 0xffff0000, v84
	v_lshlrev_b32_e32 v98, 16, v85
	v_and_b32_e32 v99, 0xffff0000, v85
	v_lshlrev_b32_e32 v96, 16, v86
	v_and_b32_e32 v97, 0xffff0000, v86
	v_lshlrev_b32_e32 v84, 16, v87
	v_and_b32_e32 v85, 0xffff0000, v87
	s_mov_b64 s[0:1], -1
	s_and_b64 vcc, exec, vcc
	s_cbranch_vccz .LBB0_660
	s_add_i32 s0, s23, s16
	v_mov_b32_e32 v86, s0
	ds_read_b32 v86, v86
	v_lshl_add_u32 v87, v212, 2, s24
	ds_read_b128 v[128:131], v87
	ds_read_b128 v[132:135], v87 offset:16
	s_mov_b64 s[0:1], 0
	s_waitcnt lgkmcnt(2)
	v_sub_f32_e32 v86, v161, v86
	v_mul_f32_e32 v86, 0x3fb8aa3b, v86
	v_exp_f32_e32 v86, v86
	s_nop 0
	v_pk_mul_f32 v[102:103], v[86:87], v[100:101] op_sel_hi:[0,1]
	v_pk_mul_f32 v[136:137], v[86:87], v[98:99] op_sel_hi:[0,1]
	v_pk_mul_f32 v[138:139], v[86:87], v[96:97] op_sel_hi:[0,1]
	v_pk_mul_f32 v[140:141], v[86:87], v[84:85] op_sel_hi:[0,1]
	s_waitcnt lgkmcnt(1)
	v_pk_mul_f32 v[86:87], v[128:129], v[102:103]
	v_pk_mul_f32 v[102:103], v[130:131], v[136:137]
	s_waitcnt lgkmcnt(0)
	v_pk_mul_f32 v[128:129], v[138:139], v[132:133]
	v_pk_mul_f32 v[130:131], v[140:141], v[134:135]

; __device__ __forceinline__ void ssd_item(const Params& P, const int pass, const int item, const int wvi) {
;     ...
; #pragma unroll
;     for (int kk = 0; kk < 4; ++kk) {
;       const int s0 = kk * 32 + fq * 8;
;       bf16x8 xf[4];
; #pragma unroll
;       for (int pt = 0; pt < 4; ++pt) {
;         const u16* xa = Xs + (kk * 32 + fq * 8 + (fr >> 2)) * LDX + pt * 16 + (fr & 3) * 4;
;         xf[pt] = cat8(ldtr(xa), ldtr(xa + 4 * LDX));
;       }
;       {
;         const u16* ba = Bs + (kk * 32 + fq * 8 + (fr >> 2)) * LDP + w * 16 + (fr & 3) * 4;
;         const s16x4 b0 = ldtr(ba), b1 = ldtr(ba + 4 * LDP);
;         const float4 wa = *(const float4*)(fww + s0), wb = *(const float4*)(fww + s0 + 4);
;         const bf16x8 af = pack8(bf2f((u16)b0[0]) * wa.x, bf2f((u16)b0[1]) * wa.y, bf2f((u16)b0[2]) * wa.z, bf2f((u16)b0[3]) * wa.w,
;                                 bf2f((u16)b1[0]) * wb.x, bf2f((u16)b1[1]) * wb.y, bf2f((u16)b1[2]) * wb.z, bf2f((u16)b1[3]) * wb.w);
; #pragma unroll
;         for (int pt = 0; pt < 4; ++pt) st[pt] = __builtin_amdgcn_mfma_f32_16x16x32_bf16(af, xf[pt], st[pt], 0, 0, 0);
;       }
;       if (kk >= kk_lo && kk <= kk_hi) {
;         const uint4 gq = (kk == 0) ? gq0 : (kk == 1) ? gq1 : (kk == 2) ? gq2 : gq3;
;         const float gv[8] = {bflo(gq.x), bfhi(gq.x), bflo(gq.y), bfhi(gq.y), bflo(gq.z), bfhi(gq.z), bflo(gq.w), bfhi(gq.w)};
;         float mv[8];
;         if (kk == (it >> 1)) {
;           const float4 ca = *(const float4*)(fcum + s0), cb = *(const float4*)(fcum + s0 + 4);
;           const float4 da = *(const float4*)(fdt + s0), db = *(const float4*)(fdt + s0 + 4);
;           const float cs[8] = {ca.x, ca.y, ca.z, ca.w, cb.x, cb.y, cb.z, cb.w};
;           const float ds[8] = {da.x, da.y, da.z, da.w, db.x, db.y, db.z, db.w};
; #pragma unroll
;           for (int e = 0; e < 8; ++e) {
;             const int ss = s0 + e;
;             const bool ok = dir ? (ss >= ii) : (ss <= ii);
;             mv[e] = ok ? gv[e] * __expf(cum_i - cs[e]) * ds[e] : 0.f;
;           }
;         } else {
;           const float ai = __expf(cum_i - fcum[dir ? kk * 32 : kk * 32 + 31]);
;           const float4 ea = *(const float4*)(fee + s0), eb = *(const float4*)(fee + s0 + 4);
;           mv[0] = gv[0] * ai * ea.x; mv[1] = gv[1] * ai * ea.y; mv[2] = gv[2] * ai * ea.z; mv[3] = gv[3] * ai * ea.w;
.LBB0_666:
	v_lshl_add_u32 v128, v212, 1, s26
	v_add_u32_e32 v234, v128, v157
	v_add_u32_e32 v236, v128, v219
	v_add_u32_e32 v182, v235, v223
	v_add_u32_e32 v136, v233, v224
	s_waitcnt lgkmcnt(1)
	v_mfma_f32_16x16x32_bf16 v[120:123], v[0:3], v[72:75], 0
	ds_read_b128 v[100:103], v234 offset:61952
	ds_read_b128 v[132:135], v236 offset:53248
	ds_read_b64_tr_b16 v[130:131], v182 offset:35392
	ds_read_b64_tr_b16 v[128:129], v136
	v_lshl_add_u32 v137, v222, 2, s25
	s_waitcnt lgkmcnt(4)
	v_mfma_f32_16x16x32_bf16 v[124:127], v[4:7], v[72:75], 0
	global_load_dwordx4 v[0:3], v247, s[98:99]
	global_load_dwordx4 v[4:7], v248, s[98:99]
	s_andn2_b64 vcc, exec, s[82:83]
	s_waitcnt lgkmcnt(0)
	v_and_b32_e32 v143, 0xffff0000, v128
	v_mfma_f32_16x16x32_bf16 v[100:103], v[100:103], v[72:75], 0
	v_lshlrev_b32_e32 v142, 16, v128
	v_mfma_f32_16x16x32_bf16 v[72:75], v[132:135], v[72:75], 0
	ds_read_b128 v[132:135], v137
	ds_read_b64_tr_b16 v[140:141], v136 offset:1088
	ds_read_b128 v[136:139], v137 offset:16
	s_waitcnt lgkmcnt(2)
	v_pk_mul_f32 v[132:133], v[132:133], v[142:143]
	s_nop 0
	v_cvt_pk_bf16_f32 v178, v132, v133
	v_and_b32_e32 v133, 0xffff0000, v129
	v_lshlrev_b32_e32 v132, 16, v129
	v_pk_mul_f32 v[128:129], v[134:135], v[132:133]
	s_nop 0
	v_cvt_pk_bf16_f32 v179, v128, v129
	s_waitcnt lgkmcnt(1)
	v_and_b32_e32 v129, 0xffff0000, v140
	v_lshlrev_b32_e32 v128, 16, v140
	s_waitcnt lgkmcnt(0)
	v_pk_mul_f32 v[128:129], v[136:137], v[128:129]
	s_nop 0
	v_cvt_pk_bf16_f32 v180, v128, v129
	v_and_b32_e32 v129, 0xffff0000, v141
	v_lshlrev_b32_e32 v128, 16, v141
	v_pk_mul_f32 v[128:129], v[138:139], v[128:129]
	s_nop 0
	v_cvt_pk_bf16_f32 v181, v128, v129
	ds_read_b64_tr_b16 v[128:129], v182 offset:34816
	ds_read_b64_tr_b16 v[140:141], v182 offset:34848
	ds_read_b64_tr_b16 v[136:137], v182 offset:34880
	ds_read_b64_tr_b16 v[132:133], v182 offset:34912
	ds_read_b64_tr_b16 v[142:143], v182 offset:35424
	ds_read_b64_tr_b16 v[138:139], v182 offset:35456
	ds_read_b64_tr_b16 v[134:135], v182 offset:35488
	s_waitcnt lgkmcnt(6)
	v_mfma_f32_16x16x32_bf16 v[112:115], v[178:181], v[128:131], v[112:115]
	s_waitcnt lgkmcnt(2)
	v_mfma_f32_16x16x32_bf16 v[116:119], v[178:181], v[140:143], v[116:119]
	s_waitcnt lgkmcnt(1)
	v_mfma_f32_16x16x32_bf16 v[104:107], v[178:181], v[136:139], v[104:107]
	s_waitcnt lgkmcnt(0)
	v_mfma_f32_16x16x32_bf16 v[108:111], v[178:181], v[132:135], v[108:111]
	ds_read_b128 v[8:11], v234 offset:53312
	ds_read_b128 v[12:15], v234 offset:57664
	s_cbranch_vccnz .LBB0_674
	v_readlane_b32 s0, v245, 12
	v_readlane_b32 s1, v245, 13
	v_lshlrev_b32_e32 v182, 16, v76
	v_and_b32_e32 v183, 0xffff0000, v76
	v_lshlrev_b32_e32 v180, 16, v77
	v_and_b32_e32 v181, 0xffff0000, v77
	v_lshlrev_b32_e32 v178, 16, v78
	v_and_b32_e32 v179, 0xffff0000, v78
	v_lshlrev_b32_e32 v76, 16, v79
	v_and_b32_e32 v77, 0xffff0000, v79
	s_andn2_b64 vcc, exec, s[0:1]
	s_mov_b64 s[0:1], -1
	s_cbranch_vccnz .LBB0_669
	s_add_i32 s0, s23, s17
	v_mov_b32_e32 v78, s0
	ds_read_b32 v78, v78
	v_lshl_add_u32 v79, v222, 2, s24
	ds_read_b128 v[184:187], v79
	ds_read_b128 v[188:191], v79 offset:16
	s_mov_b64 s[0:1], 0
	s_waitcnt lgkmcnt(2)
	v_sub_f32_e32 v78, v161, v78
	v_mul_f32_e32 v78, 0x3fb8aa3b, v78
	v_exp_f32_e32 v78, v78
	s_nop 0
	v_pk_mul_f32 v[192:193], v[78:79], v[182:183] op_sel_hi:[0,1]
	v_pk_mul_f32 v[194:195], v[78:79], v[180:181] op_sel_hi:[0,1]
	v_pk_mul_f32 v[238:239], v[78:79], v[178:179] op_sel_hi:[0,1]
	v_pk_mul_f32 v[240:241], v[78:79], v[76:77] op_sel_hi:[0,1]
	s_waitcnt lgkmcnt(1)
	v_pk_mul_f32 v[78:79], v[184:185], v[192:193]
	v_pk_mul_f32 v[184:185], v[186:187], v[194:195]
	s_waitcnt lgkmcnt(0)
	v_pk_mul_f32 v[186:187], v[238:239], v[188:189]
	v_pk_mul_f32 v[188:189], v[240:241], v[190:191]

; __device__ __forceinline__ void ssd_item(const Params& P, const int pass, const int item, const int wvi) {
;     ...
; #pragma unroll
;     for (int kk = 0; kk < 4; ++kk) {
;       const int s0 = kk * 32 + fq * 8;
;       bf16x8 xf[4];
; #pragma unroll
;       for (int pt = 0; pt < 4; ++pt) {
;         const u16* xa = Xs + (kk * 32 + fq * 8 + (fr >> 2)) * LDX + pt * 16 + (fr & 3) * 4;
;         xf[pt] = cat8(ldtr(xa), ldtr(xa + 4 * LDX));
;       }
;       {
;         const u16* ba = Bs + (kk * 32 + fq * 8 + (fr >> 2)) * LDP + w * 16 + (fr & 3) * 4;
;         const s16x4 b0 = ldtr(ba), b1 = ldtr(ba + 4 * LDP);
;         const float4 wa = *(const float4*)(fww + s0), wb = *(const float4*)(fww + s0 + 4);
;         const bf16x8 af = pack8(bf2f((u16)b0[0]) * wa.x, bf2f((u16)b0[1]) * wa.y, bf2f((u16)b0[2]) * wa.z, bf2f((u16)b0[3]) * wa.w,
;                                 bf2f((u16)b1[0]) * wb.x, bf2f((u16)b1[1]) * wb.y, bf2f((u16)b1[2]) * wb.z, bf2f((u16)b1[3]) * wb.w);
; #pragma unroll
;         for (int pt = 0; pt < 4; ++pt) st[pt] = __builtin_amdgcn_mfma_f32_16x16x32_bf16(af, xf[pt], st[pt], 0, 0, 0);
;       }
;       if (kk >= kk_lo && kk <= kk_hi) {
;         const uint4 gq = (kk == 0) ? gq0 : (kk == 1) ? gq1 : (kk == 2) ? gq2 : gq3;
;         const float gv[8] = {bflo(gq.x), bfhi(gq.x), bflo(gq.y), bfhi(gq.y), bflo(gq.z), bfhi(gq.z), bflo(gq.w), bfhi(gq.w)};
;         float mv[8];
;         if (kk == (it >> 1)) {
;           const float4 ca = *(const float4*)(fcum + s0), cb = *(const float4*)(fcum + s0 + 4);
;           const float4 da = *(const float4*)(fdt + s0), db = *(const float4*)(fdt + s0 + 4);
;           const float cs[8] = {ca.x, ca.y, ca.z, ca.w, cb.x, cb.y, cb.z, cb.w};
;           const float ds[8] = {da.x, da.y, da.z, da.w, db.x, db.y, db.z, db.w};
; #pragma unroll
;           for (int e = 0; e < 8; ++e) {
;             const int ss = s0 + e;
;             const bool ok = dir ? (ss >= ii) : (ss <= ii);
;             mv[e] = ok ? gv[e] * __expf(cum_i - cs[e]) * ds[e] : 0.f;
;           }
;         } else {
;           const float ai = __expf(cum_i - fcum[dir ? kk * 32 : kk * 32 + 31]);
;           const float4 ea = *(const float4*)(fee + s0), eb = *(const float4*)(fee + s0 + 4);
;           mv[0] = gv[0] * ai * ea.x; mv[1] = gv[1] * ai * ea.y; mv[2] = gv[2] * ai * ea.z; mv[3] = gv[3] * ai * ea.w;
.LBB0_674:
	ds_read_b128 v[132:135], v234 offset:62016
	ds_read_b128 v[136:139], v236 offset:53312
	v_add_u32_e32 v178, v235, v226
	s_andn2_b64 vcc, exec, s[2:3]
	s_waitcnt lgkmcnt(3)
	v_mfma_f32_16x16x32_bf16 v[76:79], v[8:11], v[36:39], v[120:123]
	s_waitcnt lgkmcnt(2)
	v_mfma_f32_16x16x32_bf16 v[120:123], v[12:15], v[36:39], v[124:127]
	global_load_dwordx4 v[8:11], v249, s[98:99]
	global_load_dwordx4 v[12:15], v250, s[98:99]
	v_add_u32_e32 v128, v233, v227
	s_waitcnt lgkmcnt(1)
	v_mfma_f32_16x16x32_bf16 v[100:103], v[132:135], v[36:39], v[100:103]
	v_lshl_add_u32 v134, v225, 2, s25
	ds_read_b64_tr_b16 v[126:127], v178 offset:35392
	ds_read_b64_tr_b16 v[124:125], v128
	ds_read_b64_tr_b16 v[132:133], v128 offset:1088
	ds_read_b128 v[128:131], v134
	s_waitcnt lgkmcnt(4)
	v_mfma_f32_16x16x32_bf16 v[36:39], v[136:139], v[36:39], v[72:75]
	s_waitcnt lgkmcnt(2)
	v_and_b32_e32 v135, 0xffff0000, v124
	s_nop 0
	ds_read_b128 v[72:75], v134 offset:16
	v_lshlrev_b32_e32 v134, 16, v124
	s_waitcnt lgkmcnt(1)
	v_pk_mul_f32 v[128:129], v[128:129], v[134:135]
	s_nop 0
	v_cvt_pk_bf16_f32 v140, v128, v129
	v_and_b32_e32 v129, 0xffff0000, v125
	v_lshlrev_b32_e32 v128, 16, v125
	v_pk_mul_f32 v[124:125], v[130:131], v[128:129]
	s_nop 0
	v_cvt_pk_bf16_f32 v141, v124, v125
	v_and_b32_e32 v125, 0xffff0000, v132
	v_lshlrev_b32_e32 v124, 16, v132
	s_waitcnt lgkmcnt(0)
	v_pk_mul_f32 v[72:73], v[72:73], v[124:125]
	s_nop 0
	v_cvt_pk_bf16_f32 v142, v72, v73
	v_and_b32_e32 v73, 0xffff0000, v133
	v_lshlrev_b32_e32 v72, 16, v133
	v_pk_mul_f32 v[72:73], v[74:75], v[72:73]
	ds_read_b64_tr_b16 v[124:125], v178 offset:34816
	ds_read_b64_tr_b16 v[136:137], v178 offset:34848
	ds_read_b64_tr_b16 v[132:133], v178 offset:34880
	ds_read_b64_tr_b16 v[128:129], v178 offset:34912
	ds_read_b64_tr_b16 v[138:139], v178 offset:35424
	ds_read_b64_tr_b16 v[134:135], v178 offset:35456
	ds_read_b64_tr_b16 v[130:131], v178 offset:35488
	v_cvt_pk_bf16_f32 v143, v72, v73
	s_waitcnt lgkmcnt(6)
	s_nop 0
	v_mfma_f32_16x16x32_bf16 v[72:75], v[140:143], v[124:127], v[112:115]
	s_waitcnt lgkmcnt(2)
	v_mfma_f32_16x16x32_bf16 v[116:119], v[140:143], v[136:139], v[116:119]
	s_waitcnt lgkmcnt(1)
	v_mfma_f32_16x16x32_bf16 v[104:107], v[140:143], v[132:135], v[104:107]
	s_waitcnt lgkmcnt(0)
	v_mfma_f32_16x16x32_bf16 v[108:111], v[140:143], v[128:131], v[108:111]
	ds_read_b128 v[16:19], v234 offset:53376
	ds_read_b128 v[20:23], v234 offset:57728
	s_cbranch_vccnz .LBB0_682
	v_readlane_b32 s0, v245, 14
	v_readlane_b32 s1, v245, 15
	v_lshlrev_b32_e32 v140, 16, v40
	v_and_b32_e32 v141, 0xffff0000, v40
	v_lshlrev_b32_e32 v114, 16, v41
	v_and_b32_e32 v115, 0xffff0000, v41
	v_lshlrev_b32_e32 v112, 16, v42
	v_and_b32_e32 v113, 0xffff0000, v42
	v_lshlrev_b32_e32 v40, 16, v43
	v_and_b32_e32 v41, 0xffff0000, v43
	s_andn2_b64 vcc, exec, s[0:1]
	s_mov_b64 s[0:1], -1
	s_cbranch_vccnz .LBB0_677
	s_add_i32 s0, s23, s88
	v_mov_b32_e32 v42, s0
	ds_read_b32 v42, v42
	v_lshl_add_u32 v43, v225, 2, s24
	ds_read_b128 v[178:181], v43
	ds_read_b128 v[182:185], v43 offset:16
	s_mov_b64 s[0:1], 0
	s_waitcnt lgkmcnt(2)
	v_sub_f32_e32 v42, v161, v42
	v_mul_f32_e32 v42, 0x3fb8aa3b, v42
	v_exp_f32_e32 v42, v42
	s_nop 0
	v_pk_mul_f32 v[142:143], v[42:43], v[140:141] op_sel_hi:[0,1]
	v_pk_mul_f32 v[186:187], v[42:43], v[114:115] op_sel_hi:[0,1]
	v_pk_mul_f32 v[188:189], v[42:43], v[112:113] op_sel_hi:[0,1]
	v_pk_mul_f32 v[190:191], v[42:43], v[40:41] op_sel_hi:[0,1]
	s_waitcnt lgkmcnt(1)
	v_pk_mul_f32 v[42:43], v[178:179], v[142:143]
	v_pk_mul_f32 v[142:143], v[180:181], v[186:187]
	s_waitcnt lgkmcnt(0)
	v_pk_mul_f32 v[178:179], v[188:189], v[182:183]
	v_pk_mul_f32 v[180:181], v[190:191], v[184:185]

; __device__ __forceinline__ void ssd_item(const Params& P, const int pass, const int item, const int wvi) {
;     ...
; #pragma unroll
;     for (int kk = 0; kk < 4; ++kk) {
;       const int s0 = kk * 32 + fq * 8;
;       bf16x8 xf[4];
; #pragma unroll
;       for (int pt = 0; pt < 4; ++pt) {
;         const u16* xa = Xs + (kk * 32 + fq * 8 + (fr >> 2)) * LDX + pt * 16 + (fr & 3) * 4;
;         xf[pt] = cat8(ldtr(xa), ldtr(xa + 4 * LDX));
;       }
;       {
;         const u16* ba = Bs + (kk * 32 + fq * 8 + (fr >> 2)) * LDP + w * 16 + (fr & 3) * 4;
;         const s16x4 b0 = ldtr(ba), b1 = ldtr(ba + 4 * LDP);
;         const float4 wa = *(const float4*)(fww + s0), wb = *(const float4*)(fww + s0 + 4);
;         const bf16x8 af = pack8(bf2f((u16)b0[0]) * wa.x, bf2f((u16)b0[1]) * wa.y, bf2f((u16)b0[2]) * wa.z, bf2f((u16)b0[3]) * wa.w,
;                                 bf2f((u16)b1[0]) * wb.x, bf2f((u16)b1[1]) * wb.y, bf2f((u16)b1[2]) * wb.z, bf2f((u16)b1[3]) * wb.w);
; #pragma unroll
;         for (int pt = 0; pt < 4; ++pt) st[pt] = __builtin_amdgcn_mfma_f32_16x16x32_bf16(af, xf[pt], st[pt], 0, 0, 0);
;       }
;       if (kk >= kk_lo && kk <= kk_hi) {
;         const uint4 gq = (kk == 0) ? gq0 : (kk == 1) ? gq1 : (kk == 2) ? gq2 : gq3;
;         const float gv[8] = {bflo(gq.x), bfhi(gq.x), bflo(gq.y), bfhi(gq.y), bflo(gq.z), bfhi(gq.z), bflo(gq.w), bfhi(gq.w)};
;         float mv[8];
;         if (kk == (it >> 1)) {
;           const float4 ca = *(const float4*)(fcum + s0), cb = *(const float4*)(fcum + s0 + 4);
;           const float4 da = *(const float4*)(fdt + s0), db = *(const float4*)(fdt + s0 + 4);
;           const float cs[8] = {ca.x, ca.y, ca.z, ca.w, cb.x, cb.y, cb.z, cb.w};
;           const float ds[8] = {da.x, da.y, da.z, da.w, db.x, db.y, db.z, db.w};
; #pragma unroll
;           for (int e = 0; e < 8; ++e) {
;             const int ss = s0 + e;
;             const bool ok = dir ? (ss >= ii) : (ss <= ii);
;             mv[e] = ok ? gv[e] * __expf(cum_i - cs[e]) * ds[e] : 0.f;
;           }
;         } else {
;           const float ai = __expf(cum_i - fcum[dir ? kk * 32 : kk * 32 + 31]);
;           const float4 ea = *(const float4*)(fee + s0), eb = *(const float4*)(fee + s0 + 4);
;           mv[0] = gv[0] * ai * ea.x; mv[1] = gv[1] * ai * ea.y; mv[2] = gv[2] * ai * ea.z; mv[3] = gv[3] * ai * ea.w;
.LBB0_682:
	ds_read_b128 v[128:131], v234 offset:62080
	ds_read_b128 v[132:135], v236 offset:53376
	v_add_u32_e32 v140, v235, v230
	v_lshl_add_u32 v124, v229, 2, s25
	s_waitcnt lgkmcnt(3)
	v_mfma_f32_16x16x32_bf16 v[76:79], v[16:19], v[28:31], v[76:79]
	ds_read_b64_tr_b16 v[126:127], v140 offset:35392
	s_andn2_b64 vcc, exec, s[96:97]
	s_waitcnt lgkmcnt(3)
	v_mfma_f32_16x16x32_bf16 v[40:43], v[20:23], v[28:31], v[120:123]
	global_load_dwordx4 v[16:19], v251, s[98:99]
	global_load_dwordx4 v[20:23], v252, s[98:99]
	v_add_u32_e32 v114, v233, v231
	ds_read_b64_tr_b16 v[112:113], v114
	ds_read_b64_tr_b16 v[114:115], v114 offset:1088
	s_waitcnt lgkmcnt(1)
	v_and_b32_e32 v125, 0xffff0000, v112
	v_mfma_f32_16x16x32_bf16 v[120:123], v[128:131], v[28:31], v[100:103]
	s_nop 2
	ds_read_b128 v[100:103], v124
	v_mfma_f32_16x16x32_bf16 v[28:31], v[132:135], v[28:31], v[36:39]
	s_nop 2
	ds_read_b128 v[36:39], v124 offset:16
	v_lshlrev_b32_e32 v124, 16, v112
	s_waitcnt lgkmcnt(1)
	v_pk_mul_f32 v[100:101], v[100:101], v[124:125]
	s_nop 0
	v_cvt_pk_bf16_f32 v136, v100, v101
	v_and_b32_e32 v101, 0xffff0000, v113
	v_lshlrev_b32_e32 v100, 16, v113
	v_pk_mul_f32 v[100:101], v[102:103], v[100:101]
	s_nop 0
	v_cvt_pk_bf16_f32 v137, v100, v101
	v_and_b32_e32 v101, 0xffff0000, v114
	v_lshlrev_b32_e32 v100, 16, v114
	s_waitcnt lgkmcnt(0)
	v_pk_mul_f32 v[36:37], v[36:37], v[100:101]
	s_nop 0
	v_cvt_pk_bf16_f32 v138, v36, v37
	v_and_b32_e32 v37, 0xffff0000, v115
	v_lshlrev_b32_e32 v36, 16, v115
	v_pk_mul_f32 v[36:37], v[38:39], v[36:37]
	s_nop 0
	v_cvt_pk_bf16_f32 v139, v36, v37
	ds_read_b64_tr_b16 v[124:125], v140 offset:34816
	ds_read_b64_tr_b16 v[132:133], v140 offset:34848
	ds_read_b64_tr_b16 v[128:129], v140 offset:34880
	ds_read_b64_tr_b16 v[36:37], v140 offset:34912
	ds_read_b64_tr_b16 v[134:135], v140 offset:35424
	ds_read_b64_tr_b16 v[130:131], v140 offset:35456
	ds_read_b64_tr_b16 v[38:39], v140 offset:35488
	s_waitcnt lgkmcnt(6)
	v_mfma_f32_16x16x32_bf16 v[112:115], v[136:139], v[124:127], v[72:75]
	s_waitcnt lgkmcnt(2)
	v_mfma_f32_16x16x32_bf16 v[100:103], v[136:139], v[132:135], v[116:119]
	s_waitcnt lgkmcnt(1)
	v_mfma_f32_16x16x32_bf16 v[104:107], v[136:139], v[128:131], v[104:107]
	s_waitcnt lgkmcnt(0)
	v_mfma_f32_16x16x32_bf16 v[108:111], v[136:139], v[36:39], v[108:111]
	s_cbranch_vccnz .LBB0_690
	v_readlane_b32 s0, v245, 17
	v_readlane_b32 s1, v245, 18
	v_lshlrev_b32_e32 v116, 16, v32
	v_and_b32_e32 v117, 0xffff0000, v32
	v_lshlrev_b32_e32 v74, 16, v33
	v_and_b32_e32 v75, 0xffff0000, v33
	v_lshlrev_b32_e32 v72, 16, v34
	v_and_b32_e32 v73, 0xffff0000, v34
	v_lshlrev_b32_e32 v32, 16, v35
	v_and_b32_e32 v33, 0xffff0000, v35
	s_andn2_b64 vcc, exec, s[0:1]
	s_mov_b64 s[0:1], -1
	s_cbranch_vccnz .LBB0_685
	s_add_i32 s0, s23, s89
	v_mov_b32_e32 v34, s0
	ds_read_b32 v34, v34
	v_lshl_add_u32 v35, v229, 2, s24
	ds_read_b128 v[136:139], v35
	ds_read_b128 v[140:143], v35 offset:16
	s_mov_b64 s[0:1], 0
	s_waitcnt lgkmcnt(2)
	v_sub_f32_e32 v34, v161, v34
	v_mul_f32_e32 v34, 0x3fb8aa3b, v34
	v_exp_f32_e32 v34, v34
	s_nop 0
	v_pk_mul_f32 v[118:119], v[34:35], v[116:117] op_sel_hi:[0,1]
	v_pk_mul_f32 v[178:179], v[34:35], v[74:75] op_sel_hi:[0,1]
	v_pk_mul_f32 v[180:181], v[34:35], v[72:73] op_sel_hi:[0,1]
	v_pk_mul_f32 v[182:183], v[34:35], v[32:33] op_sel_hi:[0,1]
	s_waitcnt lgkmcnt(1)
	v_pk_mul_f32 v[34:35], v[136:137], v[118:119]
	v_pk_mul_f32 v[118:119], v[138:139], v[178:179]
	s_waitcnt lgkmcnt(0)
	v_pk_mul_f32 v[136:137], v[180:181], v[140:141]
	v_pk_mul_f32 v[138:139], v[182:183], v[142:143]
